# adaLN GEMV k-loop: plain (non-nt) one-dword touches of the 7 later weight rows issued with the first row load so the serialized row loads hit L2
# baseline (speedup 1.0000x reference)
; DI void phase_ada(const float* c_in, const float* cctx_in, const float* w_ada, const float* b_ada, unsigned char* ws, unsigned char* lds) {
;     ...
;         for (int k = kg * 64; k < kg * 64 + 64; ++k) {
;             const f32x4 w = __builtin_nontemporal_load((const f32x4*)(W + (size_t)k * 6144));
; #pragma unroll
;             for (int r = 0; r < 9; ++r) { const float sv = sc[r * 1024 + k]; acc[r][0] += sv * w[0]; acc[r][1] += sv * w[1]; acc[r][2] += sv * w[2]; acc[r][3] += sv * w[3]; }
;         }
.LBB0_182:
	v_lshl_add_u64 v[48:49], v[46:47], 0, s[10:11]
	global_load_dwordx4 v[50:53], v[48:49], off nt
	v_add_co_u32_e32 v110, vcc, s27, v48
	s_nop 1
	v_addc_co_u32_e32 v111, vcc, 0, v49, vcc
	global_load_dword v112, v[110:111], off
	v_add_co_u32_e32 v110, vcc, s25, v48
	s_nop 1
	v_addc_co_u32_e32 v111, vcc, 0, v49, vcc
	global_load_dword v112, v[110:111], off
	v_add_co_u32_e32 v110, vcc, s38, v48
	s_nop 1
	v_addc_co_u32_e32 v111, vcc, 0, v49, vcc
	global_load_dword v112, v[110:111], off
	v_add_co_u32_e32 v110, vcc, s39, v48
	s_nop 1
	v_addc_co_u32_e32 v111, vcc, 0, v49, vcc
	global_load_dword v112, v[110:111], off
	v_add_co_u32_e32 v110, vcc, s78, v48
	s_nop 1
	v_addc_co_u32_e32 v111, vcc, 0, v49, vcc
	global_load_dword v112, v[110:111], off
	v_add_co_u32_e32 v110, vcc, s79, v48
	s_nop 1
	v_addc_co_u32_e32 v111, vcc, 0, v49, vcc
	global_load_dword v112, v[110:111], off
	v_add_co_u32_e32 v110, vcc, s68, v48
	s_nop 1
	v_addc_co_u32_e32 v111, vcc, 0, v49, vcc
	global_load_dword v112, v[110:111], off
	ds_read_b128 v[70:73], v68
	ds_read_b128 v[38:41], v68 offset:16
	ds_read_b128 v[54:57], v68 offset:4096
	ds_read_b128 v[78:81], v68 offset:12288
	ds_read_b128 v[82:85], v68 offset:20480
	s_waitcnt lgkmcnt(0)
	v_mov_b32_e32 v74, v70
	ds_read_b128 v[90:93], v68 offset:28672
	v_mov_b32_e32 v75, v54
	s_add_u32 s10, s10, 0x30000
	s_addc_u32 s11, s11, 0
	s_cmp_lg_u32 s10, 0x180000
	s_waitcnt lgkmcnt(0)
	v_mov_b32_e32 v104, v90
	ds_read_b128 v[94:97], v68 offset:32768
	ds_read_b128 v[86:89], v68 offset:24576
	s_waitcnt lgkmcnt(0)
	v_mov_b32_e32 v105, v94
	s_waitcnt vmcnt(0)
	v_pk_fma_f32 v[98:99], v[50:51], v[74:75], v[26:27] op_sel_hi:[0,1,1]
	v_pk_fma_f32 v[100:101], v[52:53], v[74:75], v[4:5] op_sel_hi:[0,1,1]
	ds_read_b128 v[74:77], v68 offset:8192
	v_mov_b32_e32 v4, v54
	v_mov_b32_e32 v54, v53
	v_pk_fma_f32 v[16:17], v[54:55], v[104:105], v[16:17] op_sel_hi:[0,1,1]
	s_waitcnt lgkmcnt(0)
	v_mov_b32_e32 v5, v74
	v_pk_fma_f32 v[8:9], v[50:51], v[4:5], v[8:9] op_sel:[1,0,0]
	v_pk_fma_f32 v[34:35], v[54:55], v[4:5], v[34:35] op_sel_hi:[0,1,1]
	v_mov_b32_e32 v4, v74
	v_mov_b32_e32 v5, v78
	v_pk_fma_f32 v[102:103], v[50:51], v[4:5], v[28:29] op_sel_hi:[0,1,1]
	ds_read_b128 v[26:29], v68 offset:16384
	v_pk_fma_f32 v[30:31], v[52:53], v[4:5], v[30:31] op_sel_hi:[0,1,1]
	v_mov_b32_e32 v4, v78
	v_mov_b32_e32 v74, v55
	v_mov_b32_e32 v78, v75
	s_waitcnt lgkmcnt(0)
	v_mov_b32_e32 v5, v26
	v_pk_fma_f32 v[22:23], v[50:51], v[4:5], v[22:23] op_sel:[1,0,0]
	v_pk_fma_f32 v[36:37], v[54:55], v[4:5], v[36:37] op_sel_hi:[0,1,1]
	v_mov_b32_e32 v4, v26
	v_mov_b32_e32 v5, v82
	v_pk_fma_f32 v[10:11], v[50:51], v[4:5], v[10:11] op_sel_hi:[0,1,1]
	v_pk_fma_f32 v[32:33], v[52:53], v[4:5], v[32:33] op_sel_hi:[0,1,1]
	v_mov_b32_e32 v4, v82
	v_mov_b32_e32 v5, v86
	v_pk_fma_f32 v[24:25], v[50:51], v[4:5], v[24:25] op_sel:[1,0,0]
	v_pk_fma_f32 v[14:15], v[54:55], v[4:5], v[14:15] op_sel_hi:[0,1,1]
	v_mov_b32_e32 v4, v86
	v_mov_b32_e32 v5, v90
	v_pk_fma_f32 v[12:13], v[50:51], v[4:5], v[12:13] op_sel_hi:[0,1,1]
	v_pk_fma_f32 v[18:19], v[52:53], v[4:5], v[18:19] op_sel_hi:[0,1,1]
	v_mov_b32_e32 v4, v94
	v_mov_b32_e32 v5, v70
	v_pk_fma_f32 v[6:7], v[50:51], v[4:5], v[6:7]
	v_pk_fma_f32 v[50:51], v[50:51], v[104:105], v[2:3] op_sel:[1,0,0]
	v_add_co_u32_e32 v2, vcc, s27, v48
	v_pk_fma_f32 v[20:21], v[52:53], v[4:5], v[20:21]
	s_nop 0
	v_addc_co_u32_e32 v3, vcc, 0, v49, vcc
	global_load_dwordx4 v[2:5], v[2:3], off nt
	v_mov_b32_e32 v54, v71
	v_mov_b32_e32 v26, v79
	v_mov_b32_e32 v82, v27
	v_mov_b32_e32 v86, v83
	v_mov_b32_e32 v90, v87
	v_mov_b32_e32 v70, v95
	v_mov_b32_e32 v94, v91
	s_waitcnt vmcnt(0)
	v_pk_fma_f32 v[52:53], v[2:3], v[54:55], v[98:99] op_sel_hi:[0,1,1]
	v_pk_fma_f32 v[98:99], v[4:5], v[54:55], v[100:101] op_sel_hi:[0,1,1]
	v_mov_b32_e32 v54, v5
	v_pk_fma_f32 v[8:9], v[2:3], v[74:75], v[8:9] op_sel:[1,0,0]
	v_pk_fma_f32 v[34:35], v[54:55], v[74:75], v[34:35] op_sel_hi:[0,1,1]
	v_pk_fma_f32 v[74:75], v[2:3], v[78:79], v[102:103] op_sel_hi:[0,1,1]
	v_pk_fma_f32 v[22:23], v[2:3], v[26:27], v[22:23] op_sel:[1,0,0]
	v_pk_fma_f32 v[36:37], v[54:55], v[26:27], v[36:37] op_sel_hi:[0,1,1]
	v_pk_fma_f32 v[10:11], v[2:3], v[82:83], v[10:11] op_sel_hi:[0,1,1]
	v_pk_fma_f32 v[26:27], v[4:5], v[82:83], v[32:33] op_sel_hi:[0,1,1]
	v_pk_fma_f32 v[24:25], v[2:3], v[86:87], v[24:25] op_sel:[1,0,0]
	v_pk_fma_f32 v[12:13], v[2:3], v[90:91], v[12:13] op_sel_hi:[0,1,1]
	v_pk_fma_f32 v[6:7], v[2:3], v[70:71], v[6:7]
	v_pk_fma_f32 v[32:33], v[2:3], v[94:95], v[50:51] op_sel:[1,0,0]
	v_add_co_u32_e32 v2, vcc, s25, v48
	v_pk_fma_f32 v[30:31], v[4:5], v[78:79], v[30:31] op_sel_hi:[0,1,1]
	s_nop 0
	v_addc_co_u32_e32 v3, vcc, 0, v49, vcc
	v_pk_fma_f32 v[18:19], v[4:5], v[90:91], v[18:19] op_sel_hi:[0,1,1]
	v_pk_fma_f32 v[20:21], v[4:5], v[70:71], v[20:21]
	global_load_dwordx4 v[2:5], v[2:3], off nt
	v_pk_fma_f32 v[14:15], v[54:55], v[86:87], v[14:15] op_sel_hi:[0,1,1]
	v_pk_fma_f32 v[16:17], v[54:55], v[94:95], v[16:17] op_sel_hi:[0,1,1]
	v_mov_b32_e32 v51, v56
	v_mov_b32_e32 v54, v56
	v_mov_b32_e32 v55, v76
	v_mov_b32_e32 v50, v72
	s_waitcnt vmcnt(0)
; DI void phase_ada(const float* c_in, const float* cctx_in, const float* w_ada, const float* b_ada, unsigned char* ws, unsigned char* lds) {
;     ...
;         for (int k = kg * 64; k < kg * 64 + 64; ++k) {
;             const f32x4 w = __builtin_nontemporal_load((const f32x4*)(W + (size_t)k * 6144));
; #pragma unroll
;             for (int r = 0; r < 9; ++r) { const float sv = sc[r * 1024 + k]; acc[r][0] += sv * w[0]; acc[r][1] += sv * w[1]; acc[r][2] += sv * w[2]; acc[r][3] += sv * w[3]; }
	v_mov_b32_e32 v56, v5
	v_pk_fma_f32 v[8:9], v[2:3], v[54:55], v[8:9] op_sel:[1,0,0]
	v_pk_fma_f32 v[34:35], v[56:57], v[54:55], v[34:35] op_sel_hi:[0,1,1]
	v_mov_b32_e32 v54, v76
	v_mov_b32_e32 v55, v80
	v_pk_fma_f32 v[70:71], v[2:3], v[54:55], v[74:75] op_sel_hi:[0,1,1]
	v_pk_fma_f32 v[30:31], v[4:5], v[54:55], v[30:31] op_sel_hi:[0,1,1]
	v_mov_b32_e32 v54, v80
	v_mov_b32_e32 v55, v28
	v_pk_fma_f32 v[22:23], v[2:3], v[54:55], v[22:23] op_sel:[1,0,0]
	v_pk_fma_f32 v[36:37], v[56:57], v[54:55], v[36:37] op_sel_hi:[0,1,1]
	v_mov_b32_e32 v54, v28
	v_mov_b32_e32 v55, v84
	v_pk_fma_f32 v[74:75], v[2:3], v[54:55], v[10:11] op_sel_hi:[0,1,1]
	v_mov_b32_e32 v10, v84
	v_mov_b32_e32 v11, v88
	v_pk_fma_f32 v[24:25], v[2:3], v[10:11], v[24:25] op_sel:[1,0,0]
	v_pk_fma_f32 v[14:15], v[56:57], v[10:11], v[14:15] op_sel_hi:[0,1,1]
	v_mov_b32_e32 v10, v88
	v_mov_b32_e32 v11, v92
	v_pk_fma_f32 v[78:79], v[2:3], v[10:11], v[12:13] op_sel_hi:[0,1,1]
	v_pk_fma_f32 v[18:19], v[4:5], v[10:11], v[18:19] op_sel_hi:[0,1,1]
	v_mov_b32_e32 v10, v96
	v_mov_b32_e32 v11, v72
	v_mov_b32_e32 v12, v92
	v_mov_b32_e32 v13, v96
	v_pk_fma_f32 v[52:53], v[2:3], v[50:51], v[52:53] op_sel_hi:[0,1,1]
	v_pk_fma_f32 v[6:7], v[2:3], v[10:11], v[6:7]
	v_pk_fma_f32 v[82:83], v[2:3], v[12:13], v[32:33] op_sel:[1,0,0]
	v_add_co_u32_e32 v2, vcc, s38, v48
	v_pk_fma_f32 v[50:51], v[4:5], v[50:51], v[98:99] op_sel_hi:[0,1,1]
	s_nop 0
	v_addc_co_u32_e32 v3, vcc, 0, v49, vcc
	v_pk_fma_f32 v[26:27], v[4:5], v[54:55], v[26:27] op_sel_hi:[0,1,1]
	v_pk_fma_f32 v[86:87], v[4:5], v[10:11], v[20:21]
	global_load_dwordx4 v[2:5], v[2:3], off nt
	v_mov_b32_e32 v76, v57
	v_pk_fma_f32 v[90:91], v[56:57], v[12:13], v[16:17] op_sel_hi:[0,1,1]
	v_mov_b32_e32 v56, v73
	v_mov_b32_e32 v80, v77
	v_mov_b32_e32 v28, v81
	v_mov_b32_e32 v84, v29
	v_mov_b32_e32 v88, v85
	v_mov_b32_e32 v92, v89
	v_mov_b32_e32 v72, v97
	v_mov_b32_e32 v96, v93
	v_mov_b32_e32 v99, v38
	s_waitcnt vmcnt(0)
	v_pk_fma_f32 v[54:55], v[2:3], v[76:77], v[8:9] op_sel:[1,0,0]
	v_mov_b32_e32 v8, v5
	v_pk_fma_f32 v[10:11], v[2:3], v[56:57], v[52:53] op_sel_hi:[0,1,1]
	v_pk_fma_f32 v[12:13], v[4:5], v[56:57], v[50:51] op_sel_hi:[0,1,1]
	v_pk_fma_f32 v[56:57], v[8:9], v[76:77], v[34:35] op_sel_hi:[0,1,1]
	v_pk_fma_f32 v[50:51], v[2:3], v[80:81], v[70:71] op_sel_hi:[0,1,1]
	v_pk_fma_f32 v[52:53], v[4:5], v[80:81], v[30:31] op_sel_hi:[0,1,1]
	v_pk_fma_f32 v[34:35], v[2:3], v[28:29], v[22:23] op_sel:[1,0,0]
	v_pk_fma_f32 v[36:37], v[8:9], v[28:29], v[36:37] op_sel_hi:[0,1,1]
	v_pk_fma_f32 v[30:31], v[2:3], v[84:85], v[74:75] op_sel_hi:[0,1,1]
	v_pk_fma_f32 v[32:33], v[4:5], v[84:85], v[26:27] op_sel_hi:[0,1,1]
	v_pk_fma_f32 v[26:27], v[2:3], v[88:89], v[24:25] op_sel:[1,0,0]
	v_pk_fma_f32 v[28:29], v[8:9], v[88:89], v[14:15] op_sel_hi:[0,1,1]
	v_pk_fma_f32 v[22:23], v[2:3], v[92:93], v[78:79] op_sel_hi:[0,1,1]
	v_pk_fma_f32 v[20:21], v[2:3], v[72:73], v[6:7]
	v_pk_fma_f32 v[14:15], v[2:3], v[96:97], v[82:83] op_sel:[1,0,0]
	v_add_co_u32_e32 v2, vcc, s39, v48
	v_pk_fma_f32 v[24:25], v[4:5], v[92:93], v[18:19] op_sel_hi:[0,1,1]
	s_nop 0
	v_addc_co_u32_e32 v3, vcc, 0, v49, vcc
	v_pk_fma_f32 v[16:17], v[4:5], v[72:73], v[86:87]
	global_load_dwordx4 v[2:5], v[2:3], off nt
	v_pk_fma_f32 v[18:19], v[8:9], v[96:97], v[90:91] op_sel_hi:[0,1,1]
	ds_read_b128 v[6:9], v68 offset:4112
	v_mov_b32_e32 v70, v38
	s_waitcnt lgkmcnt(0)
	v_mov_b32_e32 v71, v6
	s_waitcnt vmcnt(0)
	v_pk_fma_f32 v[86:87], v[2:3], v[70:71], v[10:11] op_sel_hi:[0,1,1]
	v_pk_fma_f32 v[88:89], v[4:5], v[70:71], v[12:13] op_sel_hi:[0,1,1]
	ds_read_b128 v[10:13], v68 offset:8208
	v_mov_b32_e32 v70, v6
	v_mov_b32_e32 v6, v5
	s_waitcnt lgkmcnt(0)
	v_mov_b32_e32 v71, v10
	v_pk_fma_f32 v[90:91], v[2:3], v[70:71], v[54:55] op_sel:[1,0,0]
	v_pk_fma_f32 v[92:93], v[6:7], v[70:71], v[56:57] op_sel_hi:[0,1,1]
	ds_read_b128 v[54:57], v68 offset:12304
	v_mov_b32_e32 v70, v10
	v_mov_b32_e32 v10, v7
	s_waitcnt lgkmcnt(0)
	v_mov_b32_e32 v71, v54
	v_pk_fma_f32 v[94:95], v[2:3], v[70:71], v[50:51] op_sel_hi:[0,1,1]
	v_pk_fma_f32 v[96:97], v[4:5], v[70:71], v[52:53] op_sel_hi:[0,1,1]
	ds_read_b128 v[50:53], v68 offset:16400
	v_mov_b32_e32 v70, v54
	v_mov_b32_e32 v54, v11
	s_waitcnt lgkmcnt(0)
	v_mov_b32_e32 v71, v50
	v_pk_fma_f32 v[34:35], v[2:3], v[70:71], v[34:35] op_sel:[1,0,0]
	v_pk_fma_f32 v[36:37], v[6:7], v[70:71], v[36:37] op_sel_hi:[0,1,1]
	ds_read_b128 v[70:73], v68 offset:20496
	v_mov_b32_e32 v74, v50
	v_mov_b32_e32 v50, v55
	s_waitcnt lgkmcnt(0)
	v_mov_b32_e32 v75, v70
	v_pk_fma_f32 v[30:31], v[2:3], v[74:75], v[30:31] op_sel_hi:[0,1,1]
	v_pk_fma_f32 v[32:33], v[4:5], v[74:75], v[32:33] op_sel_hi:[0,1,1]
	ds_read_b128 v[74:77], v68 offset:24592
	v_mov_b32_e32 v78, v70
	v_mov_b32_e32 v70, v51
	s_waitcnt lgkmcnt(0)
	v_mov_b32_e32 v79, v74
	v_pk_fma_f32 v[26:27], v[2:3], v[78:79], v[26:27] op_sel:[1,0,0]
	v_pk_fma_f32 v[28:29], v[6:7], v[78:79], v[28:29] op_sel_hi:[0,1,1]
	ds_read_b128 v[78:81], v68 offset:28688
	v_mov_b32_e32 v82, v74
	v_mov_b32_e32 v74, v71
	s_waitcnt lgkmcnt(0)
	v_mov_b32_e32 v83, v78
	v_pk_fma_f32 v[22:23], v[2:3], v[82:83], v[22:23] op_sel_hi:[0,1,1]
	v_pk_fma_f32 v[24:25], v[4:5], v[82:83], v[24:25] op_sel_hi:[0,1,1]
	ds_read_b128 v[82:85], v68 offset:32784
	v_mov_b32_e32 v100, v78
	v_mov_b32_e32 v78, v75
	v_add_u32_e32 v68, 32, v68
	s_waitcnt lgkmcnt(0)
	v_mov_b32_e32 v98, v82
	v_mov_b32_e32 v101, v82
	v_pk_fma_f32 v[20:21], v[2:3], v[98:99], v[20:21]
	v_pk_fma_f32 v[14:15], v[2:3], v[100:101], v[14:15] op_sel:[1,0,0]
	v_add_co_u32_e32 v2, vcc, s78, v48
	v_pk_fma_f32 v[16:17], v[4:5], v[98:99], v[16:17]
	s_nop 0
	v_addc_co_u32_e32 v3, vcc, 0, v49, vcc
	global_load_dwordx4 v[2:5], v[2:3], off nt
	v_pk_fma_f32 v[18:19], v[6:7], v[100:101], v[18:19] op_sel_hi:[0,1,1]
	v_mov_b32_e32 v6, v39
	v_mov_b32_e32 v38, v83
	v_mov_b32_e32 v82, v79
	s_waitcnt vmcnt(0)
; DI void phase_ada(const float* c_in, const float* cctx_in, const float* w_ada, const float* b_ada, unsigned char* ws, unsigned char* lds) {
;     ...
;         for (int k = kg * 64; k < kg * 64 + 64; ++k) {
;             const f32x4 w = __builtin_nontemporal_load((const f32x4*)(W + (size_t)k * 6144));
; #pragma unroll
;             for (int r = 0; r < 9; ++r) { const float sv = sc[r * 1024 + k]; acc[r][0] += sv * w[0]; acc[r][1] += sv * w[1]; acc[r][2] += sv * w[2]; acc[r][3] += sv * w[3]; }
;         }
; #pragma unroll
;         for (int r = 0; r < 9; ++r)
; #pragma unroll
;             for (int j = 0; j < 4; ++j) red[(kg * 128 + c4 + j) * 9 + r] = acc[r][j];
;         __syncthreads();
;         if (tid < 128) {
	v_pk_fma_f32 v[86:87], v[2:3], v[6:7], v[86:87] op_sel_hi:[0,1,1]
	v_pk_fma_f32 v[88:89], v[4:5], v[6:7], v[88:89] op_sel_hi:[0,1,1]
	v_pk_fma_f32 v[6:7], v[2:3], v[10:11], v[90:91] op_sel:[1,0,0]
	v_mov_b32_e32 v90, v5
	v_pk_fma_f32 v[92:93], v[90:91], v[10:11], v[92:93] op_sel_hi:[0,1,1]
	v_pk_fma_f32 v[10:11], v[2:3], v[54:55], v[94:95] op_sel_hi:[0,1,1]
	v_pk_fma_f32 v[34:35], v[2:3], v[50:51], v[34:35] op_sel:[1,0,0]
	v_pk_fma_f32 v[30:31], v[2:3], v[70:71], v[30:31] op_sel_hi:[0,1,1]
	v_pk_fma_f32 v[26:27], v[2:3], v[74:75], v[26:27] op_sel:[1,0,0]
	v_pk_fma_f32 v[22:23], v[2:3], v[78:79], v[22:23] op_sel_hi:[0,1,1]
	v_pk_fma_f32 v[20:21], v[2:3], v[38:39], v[20:21]
	v_pk_fma_f32 v[14:15], v[2:3], v[82:83], v[14:15] op_sel:[1,0,0]
	v_add_co_u32_e32 v2, vcc, s79, v48
	v_pk_fma_f32 v[94:95], v[4:5], v[54:55], v[96:97] op_sel_hi:[0,1,1]
	s_nop 0
	v_addc_co_u32_e32 v3, vcc, 0, v49, vcc
	v_pk_fma_f32 v[32:33], v[4:5], v[70:71], v[32:33] op_sel_hi:[0,1,1]
	v_pk_fma_f32 v[24:25], v[4:5], v[78:79], v[24:25] op_sel_hi:[0,1,1]
	v_pk_fma_f32 v[16:17], v[4:5], v[38:39], v[16:17]
	global_load_dwordx4 v[2:5], v[2:3], off nt
	v_pk_fma_f32 v[36:37], v[90:91], v[50:51], v[36:37] op_sel_hi:[0,1,1]
	v_mov_b32_e32 v39, v8
	v_mov_b32_e32 v50, v8
	v_mov_b32_e32 v51, v12
	v_pk_fma_f32 v[28:29], v[90:91], v[74:75], v[28:29] op_sel_hi:[0,1,1]
	v_pk_fma_f32 v[18:19], v[90:91], v[82:83], v[18:19] op_sel_hi:[0,1,1]
	v_mov_b32_e32 v38, v40
	s_waitcnt vmcnt(0)
	v_mov_b32_e32 v8, v5
	v_pk_fma_f32 v[6:7], v[2:3], v[50:51], v[6:7] op_sel:[1,0,0]
	v_pk_fma_f32 v[70:71], v[8:9], v[50:51], v[92:93] op_sel_hi:[0,1,1]
	v_mov_b32_e32 v50, v12
	v_mov_b32_e32 v51, v56
	v_pk_fma_f32 v[10:11], v[2:3], v[50:51], v[10:11] op_sel_hi:[0,1,1]
	v_pk_fma_f32 v[74:75], v[4:5], v[50:51], v[94:95] op_sel_hi:[0,1,1]
	v_mov_b32_e32 v50, v56
	v_mov_b32_e32 v51, v52
	v_pk_fma_f32 v[78:79], v[2:3], v[50:51], v[34:35] op_sel:[1,0,0]
	v_mov_b32_e32 v34, v52
	v_mov_b32_e32 v35, v72
	v_pk_fma_f32 v[82:83], v[2:3], v[34:35], v[30:31] op_sel_hi:[0,1,1]
	v_mov_b32_e32 v30, v72
	v_mov_b32_e32 v31, v76
	v_pk_fma_f32 v[54:55], v[2:3], v[38:39], v[86:87] op_sel_hi:[0,1,1]
	v_pk_fma_f32 v[86:87], v[2:3], v[30:31], v[26:27] op_sel:[1,0,0]
	v_mov_b32_e32 v26, v76
	v_mov_b32_e32 v27, v80
	v_pk_fma_f32 v[90:91], v[2:3], v[26:27], v[22:23] op_sel_hi:[0,1,1]
	v_mov_b32_e32 v22, v84
	v_mov_b32_e32 v23, v40
	v_pk_fma_f32 v[38:39], v[4:5], v[38:39], v[88:89] op_sel_hi:[0,1,1]
	v_pk_fma_f32 v[32:33], v[4:5], v[34:35], v[32:33] op_sel_hi:[0,1,1]
	v_pk_fma_f32 v[92:93], v[4:5], v[26:27], v[24:25] op_sel_hi:[0,1,1]
	v_pk_fma_f32 v[16:17], v[4:5], v[22:23], v[16:17]
	v_add_co_u32_e32 v4, vcc, s68, v48
	v_pk_fma_f32 v[36:37], v[8:9], v[50:51], v[36:37] op_sel_hi:[0,1,1]
	s_nop 0
	v_addc_co_u32_e32 v5, vcc, 0, v49, vcc
	global_load_dwordx4 v[48:51], v[4:5], off nt
	v_mov_b32_e32 v24, v80
	v_mov_b32_e32 v25, v84
	v_pk_fma_f32 v[88:89], v[8:9], v[30:31], v[28:29] op_sel_hi:[0,1,1]
	v_pk_fma_f32 v[94:95], v[8:9], v[24:25], v[18:19] op_sel_hi:[0,1,1]
	v_mov_b32_e32 v8, v41
	v_pk_fma_f32 v[20:21], v[2:3], v[22:23], v[20:21]
	v_pk_fma_f32 v[2:3], v[2:3], v[24:25], v[14:15] op_sel:[1,0,0]
	v_mov_b32_e32 v12, v9
	v_mov_b32_e32 v56, v13
	v_mov_b32_e32 v52, v57
	v_mov_b32_e32 v72, v53
	v_mov_b32_e32 v76, v73
	v_mov_b32_e32 v80, v77
	v_mov_b32_e32 v40, v85
	v_mov_b32_e32 v84, v81
	s_waitcnt vmcnt(0)
	v_pk_fma_f32 v[4:5], v[50:51], v[8:9], v[38:39] op_sel_hi:[0,1,1]
	v_mov_b32_e32 v38, v51
	v_pk_fma_f32 v[26:27], v[48:49], v[8:9], v[54:55] op_sel_hi:[0,1,1]
	v_pk_fma_f32 v[8:9], v[48:49], v[12:13], v[6:7] op_sel:[1,0,0]
	v_pk_fma_f32 v[34:35], v[38:39], v[12:13], v[70:71] op_sel_hi:[0,1,1]
	v_pk_fma_f32 v[28:29], v[48:49], v[56:57], v[10:11] op_sel_hi:[0,1,1]
	v_pk_fma_f32 v[30:31], v[50:51], v[56:57], v[74:75] op_sel_hi:[0,1,1]
	v_pk_fma_f32 v[22:23], v[48:49], v[52:53], v[78:79] op_sel:[1,0,0]
	v_pk_fma_f32 v[36:37], v[38:39], v[52:53], v[36:37] op_sel_hi:[0,1,1]
	v_pk_fma_f32 v[10:11], v[48:49], v[72:73], v[82:83] op_sel_hi:[0,1,1]
	v_pk_fma_f32 v[32:33], v[50:51], v[72:73], v[32:33] op_sel_hi:[0,1,1]
	v_pk_fma_f32 v[24:25], v[48:49], v[76:77], v[86:87] op_sel:[1,0,0]
	v_pk_fma_f32 v[14:15], v[38:39], v[76:77], v[88:89] op_sel_hi:[0,1,1]
	v_pk_fma_f32 v[12:13], v[48:49], v[80:81], v[90:91] op_sel_hi:[0,1,1]
	v_pk_fma_f32 v[18:19], v[50:51], v[80:81], v[92:93] op_sel_hi:[0,1,1]
	v_pk_fma_f32 v[6:7], v[48:49], v[40:41], v[20:21]
	v_pk_fma_f32 v[2:3], v[48:49], v[84:85], v[2:3] op_sel:[1,0,0]
	v_pk_fma_f32 v[20:21], v[50:51], v[40:41], v[16:17]
	v_pk_fma_f32 v[16:17], v[38:39], v[84:85], v[94:95] op_sel_hi:[0,1,1]
	s_cbranch_scc1 .LBB0_182
	ds_write_b128 v58, v[26:29] offset:36864
	ds_write_b128 v58, v[34:37] offset:36976
	ds_write_b128 v58, v[30:33] offset:36944
	ds_write_b128 v58, v[22:25] offset:36912
	ds_write_b128 v58, v[10:13] offset:36880
	ds_write_b128 v58, v[6:9] offset:36896
	ds_write_b128 v58, v[2:5] offset:36928
	ds_write_b128 v58, v[18:21] offset:36960
	ds_write_b128 v58, v[14:17] offset:36992
	s_waitcnt lgkmcnt(0)
	s_barrier
	s_and_saveexec_b64 s[10:11], s[40:41]
	s_cbranch_execz .LBB0_180
; DI void phase_ada(const float* c_in, const float* cctx_in, const float* w_ada, const float* b_ada, unsigned char* ws, unsigned char* lds) {
;     ...
;         if (tid < 128) {
;             const int col = cgp * 128 + tid;
;             const float bb = b_ada[l * 6144 + col];
; #pragma unroll
;             for (int r = 0; r < 9; ++r) {
;                 float s = 0.f;
; #pragma unroll
;                 for (int g = 0; g < 16; ++g) s += red[(g * 128 + tid) * 9 + r];
;                 modt[((size_t)l * 9 + r) * 6144 + col] = s + bb;
;             }
	v_add_u32_e32 v2, s8, v42
	s_mul_i32 s4, s3, 0x1800
	v_add_u32_e32 v4, s4, v2
	v_ashrrev_i32_e32 v5, 31, v4
	v_lshl_add_u64 v[4:5], v[4:5], 2, s[6:7]
	global_load_dword v6, v[4:5], off
	ds_read_b32 v4, v0 offset:36864
	ds_read_b32 v5, v0 offset:41472
	v_ashrrev_i32_e32 v3, 31, v2
	s_mul_i32 s3, s3, 9
	v_lshl_add_u64 v[2:3], v[2:3], 2, s[12:13]
	s_waitcnt lgkmcnt(1)
	v_add_f32_e32 v4, 0, v4
	s_waitcnt lgkmcnt(0)
	v_add_f32_e32 v4, v4, v5
	ds_read_b32 v5, v0 offset:46080
	v_mad_i64_i32 v[2:3], s[4:5], s3, v184, v[2:3]
	s_waitcnt lgkmcnt(0)
	v_add_f32_e32 v4, v4, v5
	ds_read_b32 v5, v0 offset:50688
	s_waitcnt lgkmcnt(0)
	v_add_f32_e32 v4, v4, v5
	ds_read_b32 v5, v0 offset:55296
	s_waitcnt lgkmcnt(0)
	v_add_f32_e32 v4, v4, v5
	ds_read_b32 v5, v0 offset:59904
	s_waitcnt lgkmcnt(0)
	v_add_f32_e32 v4, v4, v5
	ds_read_b32 v5, v0 offset:64512
	s_waitcnt lgkmcnt(0)
	v_add_f32_e32 v4, v4, v5
	ds_read_b32 v5, v59 offset:36864
	s_waitcnt lgkmcnt(0)
	v_add_f32_e32 v4, v4, v5
	ds_read_b32 v5, v60 offset:36864
	s_waitcnt lgkmcnt(0)
	v_add_f32_e32 v4, v4, v5
	ds_read_b32 v5, v61 offset:36864
	s_waitcnt lgkmcnt(0)
	v_add_f32_e32 v4, v4, v5
	ds_read_b32 v5, v62 offset:36864
	s_waitcnt lgkmcnt(0)
	v_add_f32_e32 v4, v4, v5
	ds_read_b32 v5, v63 offset:36864
	s_waitcnt lgkmcnt(0)
	v_add_f32_e32 v4, v4, v5
	ds_read_b32 v5, v64 offset:36864
	s_waitcnt lgkmcnt(0)
	v_add_f32_e32 v4, v4, v5
	ds_read_b32 v5, v65 offset:36864
	s_waitcnt lgkmcnt(0)
	v_add_f32_e32 v4, v4, v5
	ds_read_b32 v5, v66 offset:36864
	s_waitcnt lgkmcnt(0)
	v_add_f32_e32 v4, v4, v5
	ds_read_b32 v5, v67 offset:36864
	s_waitcnt lgkmcnt(0)
	v_add_f32_e32 v4, v4, v5
	s_waitcnt vmcnt(0)
	v_add_f32_e32 v4, v6, v4
	flat_store_dword v[2:3], v4
	ds_read_b32 v4, v0 offset:36868
	ds_read_b32 v5, v0 offset:41476
	s_waitcnt lgkmcnt(0)
	v_add_f32_e32 v4, 0, v4
	v_add_f32_e32 v4, v4, v5
	ds_read_b32 v5, v0 offset:46084
	s_waitcnt lgkmcnt(0)
	v_add_f32_e32 v4, v4, v5
	ds_read_b32 v5, v0 offset:50692
	s_waitcnt lgkmcnt(0)
	v_add_f32_e32 v4, v4, v5
	ds_read_b32 v5, v0 offset:55300
	s_waitcnt lgkmcnt(0)
	v_add_f32_e32 v4, v4, v5
	ds_read_b32 v5, v0 offset:59908
	s_waitcnt lgkmcnt(0)
	v_add_f32_e32 v4, v4, v5
	ds_read_b32 v5, v0 offset:64516
	s_waitcnt lgkmcnt(0)
	v_add_f32_e32 v4, v4, v5
	ds_read_b32 v5, v59 offset:36868
	s_waitcnt lgkmcnt(0)
	v_add_f32_e32 v4, v4, v5
	ds_read_b32 v5, v60 offset:36868
	s_waitcnt lgkmcnt(0)
	v_add_f32_e32 v4, v4, v5
	ds_read_b32 v5, v61 offset:36868
	s_waitcnt lgkmcnt(0)
	v_add_f32_e32 v4, v4, v5
	ds_read_b32 v5, v62 offset:36868
	s_waitcnt lgkmcnt(0)
	v_add_f32_e32 v4, v4, v5
	ds_read_b32 v5, v63 offset:36868
	s_waitcnt lgkmcnt(0)
	v_add_f32_e32 v4, v4, v5
	ds_read_b32 v5, v64 offset:36868
	s_waitcnt lgkmcnt(0)
	v_add_f32_e32 v4, v4, v5
	ds_read_b32 v5, v65 offset:36868
	s_waitcnt lgkmcnt(0)
	v_add_f32_e32 v4, v4, v5
	ds_read_b32 v5, v66 offset:36868
	s_waitcnt lgkmcnt(0)
	v_add_f32_e32 v4, v4, v5
	ds_read_b32 v5, v67 offset:36868
	s_waitcnt lgkmcnt(0)
	v_add_f32_e32 v4, v4, v5
	v_add_f32_e32 v7, v6, v4
	v_add_co_u32_e32 v4, vcc, s27, v2
	s_nop 1
	v_addc_co_u32_e32 v5, vcc, 0, v3, vcc
	flat_store_dword v[4:5], v7
	ds_read_b32 v4, v0 offset:36872
	ds_read_b32 v5, v0 offset:41480
	s_waitcnt lgkmcnt(0)
	v_add_f32_e32 v4, 0, v4
	v_add_f32_e32 v4, v4, v5
	ds_read_b32 v5, v0 offset:46088
	s_waitcnt lgkmcnt(0)
	v_add_f32_e32 v4, v4, v5
	ds_read_b32 v5, v0 offset:50696
	s_waitcnt lgkmcnt(0)
	v_add_f32_e32 v4, v4, v5
	ds_read_b32 v5, v0 offset:55304
	s_waitcnt lgkmcnt(0)
	v_add_f32_e32 v4, v4, v5
	ds_read_b32 v5, v0 offset:59912
	s_waitcnt lgkmcnt(0)
	v_add_f32_e32 v4, v4, v5
	ds_read_b32 v5, v0 offset:64520
	s_waitcnt lgkmcnt(0)
	v_add_f32_e32 v4, v4, v5
	ds_read_b32 v5, v59 offset:36872
	s_waitcnt lgkmcnt(0)
	v_add_f32_e32 v4, v4, v5
	ds_read_b32 v5, v60 offset:36872
	s_waitcnt lgkmcnt(0)
	v_add_f32_e32 v4, v4, v5
	ds_read_b32 v5, v61 offset:36872
	s_waitcnt lgkmcnt(0)
	v_add_f32_e32 v4, v4, v5
	ds_read_b32 v5, v62 offset:36872
	s_waitcnt lgkmcnt(0)
	v_add_f32_e32 v4, v4, v5
	ds_read_b32 v5, v63 offset:36872
	s_waitcnt lgkmcnt(0)
	v_add_f32_e32 v4, v4, v5
	ds_read_b32 v5, v64 offset:36872
	s_waitcnt lgkmcnt(0)
	v_add_f32_e32 v4, v4, v5
	ds_read_b32 v5, v65 offset:36872
	s_waitcnt lgkmcnt(0)
	v_add_f32_e32 v4, v4, v5
	ds_read_b32 v5, v66 offset:36872
	s_waitcnt lgkmcnt(0)
	v_add_f32_e32 v4, v4, v5
	ds_read_b32 v5, v67 offset:36872
	s_waitcnt lgkmcnt(0)
	v_add_f32_e32 v4, v4, v5
	v_add_f32_e32 v7, v6, v4
	v_add_co_u32_e32 v4, vcc, s25, v2
	s_nop 1
	v_addc_co_u32_e32 v5, vcc, 0, v3, vcc
	flat_store_dword v[4:5], v7
	ds_read_b32 v4, v0 offset:36876
	ds_read_b32 v5, v0 offset:41484
	s_waitcnt lgkmcnt(0)
	v_add_f32_e32 v4, 0, v4
	v_add_f32_e32 v4, v4, v5
	ds_read_b32 v5, v0 offset:46092
	s_waitcnt lgkmcnt(0)
	v_add_f32_e32 v4, v4, v5
	ds_read_b32 v5, v0 offset:50700
	s_waitcnt lgkmcnt(0)
	v_add_f32_e32 v4, v4, v5
	ds_read_b32 v5, v0 offset:55308
	s_waitcnt lgkmcnt(0)
	v_add_f32_e32 v4, v4, v5
	ds_read_b32 v5, v0 offset:59916
	s_waitcnt lgkmcnt(0)
	v_add_f32_e32 v4, v4, v5
	ds_read_b32 v5, v0 offset:64524
	s_waitcnt lgkmcnt(0)
	v_add_f32_e32 v4, v4, v5
	ds_read_b32 v5, v59 offset:36876
	s_waitcnt lgkmcnt(0)
	v_add_f32_e32 v4, v4, v5
	ds_read_b32 v5, v60 offset:36876
	s_waitcnt lgkmcnt(0)
	v_add_f32_e32 v4, v4, v5
	ds_read_b32 v5, v61 offset:36876
	s_waitcnt lgkmcnt(0)
	v_add_f32_e32 v4, v4, v5
	ds_read_b32 v5, v62 offset:36876
	s_waitcnt lgkmcnt(0)
	v_add_f32_e32 v4, v4, v5
	ds_read_b32 v5, v63 offset:36876
	s_waitcnt lgkmcnt(0)
	v_add_f32_e32 v4, v4, v5
	ds_read_b32 v5, v64 offset:36876
	s_waitcnt lgkmcnt(0)
	v_add_f32_e32 v4, v4, v5
	ds_read_b32 v5, v65 offset:36876
	s_waitcnt lgkmcnt(0)
; DI void phase_ada(const float* c_in, const float* cctx_in, const float* w_ada, const float* b_ada, unsigned char* ws, unsigned char* lds) {
;     ...
;         if (tid < 128) {
;             const int col = cgp * 128 + tid;
;             const float bb = b_ada[l * 6144 + col];
; #pragma unroll
;             for (int r = 0; r < 9; ++r) {
;                 float s = 0.f;
; #pragma unroll
;                 for (int g = 0; g < 16; ++g) s += red[(g * 128 + tid) * 9 + r];
;                 modt[((size_t)l * 9 + r) * 6144 + col] = s + bb;
;             }
	v_add_f32_e32 v4, v4, v5
	ds_read_b32 v5, v66 offset:36876
	s_waitcnt lgkmcnt(0)
	v_add_f32_e32 v4, v4, v5
	ds_read_b32 v5, v67 offset:36876
	s_waitcnt lgkmcnt(0)
	v_add_f32_e32 v4, v4, v5
	v_add_f32_e32 v7, v6, v4
	v_add_co_u32_e32 v4, vcc, s38, v2
	s_nop 1
	v_addc_co_u32_e32 v5, vcc, 0, v3, vcc
	flat_store_dword v[4:5], v7
	ds_read_b32 v4, v0 offset:36880
	ds_read_b32 v5, v0 offset:41488
	s_waitcnt lgkmcnt(0)
	v_add_f32_e32 v4, 0, v4
	v_add_f32_e32 v4, v4, v5
	ds_read_b32 v5, v0 offset:46096
	s_waitcnt lgkmcnt(0)
	v_add_f32_e32 v4, v4, v5
	ds_read_b32 v5, v0 offset:50704
	s_waitcnt lgkmcnt(0)
	v_add_f32_e32 v4, v4, v5
	ds_read_b32 v5, v0 offset:55312
	s_waitcnt lgkmcnt(0)
	v_add_f32_e32 v4, v4, v5
	ds_read_b32 v5, v0 offset:59920
	s_waitcnt lgkmcnt(0)
	v_add_f32_e32 v4, v4, v5
	ds_read_b32 v5, v0 offset:64528
	s_waitcnt lgkmcnt(0)
	v_add_f32_e32 v4, v4, v5
	ds_read_b32 v5, v59 offset:36880
	s_waitcnt lgkmcnt(0)
	v_add_f32_e32 v4, v4, v5
	ds_read_b32 v5, v60 offset:36880
	s_waitcnt lgkmcnt(0)
	v_add_f32_e32 v4, v4, v5
	ds_read_b32 v5, v61 offset:36880
	s_waitcnt lgkmcnt(0)
	v_add_f32_e32 v4, v4, v5
	ds_read_b32 v5, v62 offset:36880
	s_waitcnt lgkmcnt(0)
	v_add_f32_e32 v4, v4, v5
	ds_read_b32 v5, v63 offset:36880
	s_waitcnt lgkmcnt(0)
	v_add_f32_e32 v4, v4, v5
	ds_read_b32 v5, v64 offset:36880
	s_waitcnt lgkmcnt(0)
	v_add_f32_e32 v4, v4, v5
	ds_read_b32 v5, v65 offset:36880
	s_waitcnt lgkmcnt(0)
	v_add_f32_e32 v4, v4, v5
	ds_read_b32 v5, v66 offset:36880
	s_waitcnt lgkmcnt(0)
	v_add_f32_e32 v4, v4, v5
	ds_read_b32 v5, v67 offset:36880
	s_waitcnt lgkmcnt(0)
	v_add_f32_e32 v4, v4, v5
	v_add_f32_e32 v7, v6, v4
	v_add_co_u32_e32 v4, vcc, s39, v2
	s_nop 1
	v_addc_co_u32_e32 v5, vcc, 0, v3, vcc
	flat_store_dword v[4:5], v7
	ds_read_b32 v4, v0 offset:36884
	ds_read_b32 v5, v0 offset:41492
	s_waitcnt lgkmcnt(0)
	v_add_f32_e32 v4, 0, v4
	v_add_f32_e32 v4, v4, v5
	ds_read_b32 v5, v0 offset:46100
	s_waitcnt lgkmcnt(0)
	v_add_f32_e32 v4, v4, v5
	ds_read_b32 v5, v0 offset:50708
	s_waitcnt lgkmcnt(0)
	v_add_f32_e32 v4, v4, v5
	ds_read_b32 v5, v0 offset:55316
	s_waitcnt lgkmcnt(0)
	v_add_f32_e32 v4, v4, v5
	ds_read_b32 v5, v0 offset:59924
	s_waitcnt lgkmcnt(0)
	v_add_f32_e32 v4, v4, v5
	ds_read_b32 v5, v0 offset:64532
	s_waitcnt lgkmcnt(0)
	v_add_f32_e32 v4, v4, v5
	ds_read_b32 v5, v59 offset:36884
	s_waitcnt lgkmcnt(0)
	v_add_f32_e32 v4, v4, v5
	ds_read_b32 v5, v60 offset:36884
	s_waitcnt lgkmcnt(0)
	v_add_f32_e32 v4, v4, v5
	ds_read_b32 v5, v61 offset:36884
	s_waitcnt lgkmcnt(0)
	v_add_f32_e32 v4, v4, v5
	ds_read_b32 v5, v62 offset:36884
	s_waitcnt lgkmcnt(0)
	v_add_f32_e32 v4, v4, v5
	ds_read_b32 v5, v63 offset:36884
	s_waitcnt lgkmcnt(0)
	v_add_f32_e32 v4, v4, v5
	ds_read_b32 v5, v64 offset:36884
	s_waitcnt lgkmcnt(0)
	v_add_f32_e32 v4, v4, v5
	ds_read_b32 v5, v65 offset:36884
	s_waitcnt lgkmcnt(0)
	v_add_f32_e32 v4, v4, v5
	ds_read_b32 v5, v66 offset:36884
	s_waitcnt lgkmcnt(0)
	v_add_f32_e32 v4, v4, v5
	ds_read_b32 v5, v67 offset:36884
	s_waitcnt lgkmcnt(0)
	v_add_f32_e32 v4, v4, v5
	v_add_f32_e32 v7, v6, v4
	v_add_co_u32_e32 v4, vcc, s78, v2
	s_nop 1
	v_addc_co_u32_e32 v5, vcc, 0, v3, vcc
	flat_store_dword v[4:5], v7
	ds_read_b32 v4, v0 offset:36888
	ds_read_b32 v5, v0 offset:41496
	s_waitcnt lgkmcnt(0)
	v_add_f32_e32 v4, 0, v4
	v_add_f32_e32 v4, v4, v5
	ds_read_b32 v5, v0 offset:46104
	s_waitcnt lgkmcnt(0)
	v_add_f32_e32 v4, v4, v5
	ds_read_b32 v5, v0 offset:50712
	s_waitcnt lgkmcnt(0)
	v_add_f32_e32 v4, v4, v5
	ds_read_b32 v5, v0 offset:55320
	s_waitcnt lgkmcnt(0)
	v_add_f32_e32 v4, v4, v5
	ds_read_b32 v5, v0 offset:59928
	s_waitcnt lgkmcnt(0)
	v_add_f32_e32 v4, v4, v5
	ds_read_b32 v5, v0 offset:64536
	s_waitcnt lgkmcnt(0)
; DI void phase_ada(const float* c_in, const float* cctx_in, const float* w_ada, const float* b_ada, unsigned char* ws, unsigned char* lds) {
;     ...
;         if (tid < 128) {
;             const int col = cgp * 128 + tid;
;             const float bb = b_ada[l * 6144 + col];
; #pragma unroll
;             for (int r = 0; r < 9; ++r) {
;                 float s = 0.f;
; #pragma unroll
;                 for (int g = 0; g < 16; ++g) s += red[(g * 128 + tid) * 9 + r];
;                 modt[((size_t)l * 9 + r) * 6144 + col] = s + bb;
;             }
	v_add_f32_e32 v4, v4, v5
	ds_read_b32 v5, v59 offset:36888
	s_waitcnt lgkmcnt(0)
	v_add_f32_e32 v4, v4, v5
	ds_read_b32 v5, v60 offset:36888
	s_waitcnt lgkmcnt(0)
	v_add_f32_e32 v4, v4, v5
	ds_read_b32 v5, v61 offset:36888
	s_waitcnt lgkmcnt(0)
	v_add_f32_e32 v4, v4, v5
	ds_read_b32 v5, v62 offset:36888
	s_waitcnt lgkmcnt(0)
	v_add_f32_e32 v4, v4, v5
	ds_read_b32 v5, v63 offset:36888
	s_waitcnt lgkmcnt(0)
	v_add_f32_e32 v4, v4, v5
	ds_read_b32 v5, v64 offset:36888
	s_waitcnt lgkmcnt(0)
	v_add_f32_e32 v4, v4, v5
	ds_read_b32 v5, v65 offset:36888
	s_waitcnt lgkmcnt(0)
	v_add_f32_e32 v4, v4, v5
	ds_read_b32 v5, v66 offset:36888
	s_waitcnt lgkmcnt(0)
	v_add_f32_e32 v4, v4, v5
	ds_read_b32 v5, v67 offset:36888
	s_waitcnt lgkmcnt(0)
	v_add_f32_e32 v4, v4, v5
	v_add_f32_e32 v7, v6, v4
	v_add_co_u32_e32 v4, vcc, s79, v2
	s_nop 1
	v_addc_co_u32_e32 v5, vcc, 0, v3, vcc
	flat_store_dword v[4:5], v7
	ds_read_b32 v4, v0 offset:36892
	ds_read_b32 v5, v0 offset:41500
	s_waitcnt lgkmcnt(0)
	v_add_f32_e32 v4, 0, v4
	v_add_f32_e32 v4, v4, v5
	ds_read_b32 v5, v0 offset:46108
	s_waitcnt lgkmcnt(0)
	v_add_f32_e32 v4, v4, v5
	ds_read_b32 v5, v0 offset:50716
	s_waitcnt lgkmcnt(0)
	v_add_f32_e32 v4, v4, v5
	ds_read_b32 v5, v0 offset:55324
	s_waitcnt lgkmcnt(0)
	v_add_f32_e32 v4, v4, v5
	ds_read_b32 v5, v0 offset:59932
	s_waitcnt lgkmcnt(0)
	v_add_f32_e32 v4, v4, v5
	ds_read_b32 v5, v0 offset:64540
	s_waitcnt lgkmcnt(0)
	v_add_f32_e32 v4, v4, v5
	ds_read_b32 v5, v59 offset:36892
	s_waitcnt lgkmcnt(0)
	v_add_f32_e32 v4, v4, v5
	ds_read_b32 v5, v60 offset:36892
	s_waitcnt lgkmcnt(0)
	v_add_f32_e32 v4, v4, v5
	ds_read_b32 v5, v61 offset:36892
	s_waitcnt lgkmcnt(0)
	v_add_f32_e32 v4, v4, v5
	ds_read_b32 v5, v62 offset:36892
	s_waitcnt lgkmcnt(0)
	v_add_f32_e32 v4, v4, v5
	ds_read_b32 v5, v63 offset:36892
	s_waitcnt lgkmcnt(0)
	v_add_f32_e32 v4, v4, v5
	ds_read_b32 v5, v64 offset:36892
	s_waitcnt lgkmcnt(0)
	v_add_f32_e32 v4, v4, v5
	ds_read_b32 v5, v65 offset:36892
	s_waitcnt lgkmcnt(0)
	v_add_f32_e32 v4, v4, v5
	ds_read_b32 v5, v66 offset:36892
	s_waitcnt lgkmcnt(0)
	v_add_f32_e32 v4, v4, v5
	ds_read_b32 v5, v67 offset:36892
	s_waitcnt lgkmcnt(0)
	v_add_f32_e32 v4, v4, v5
	v_add_f32_e32 v7, v6, v4
	v_add_co_u32_e32 v4, vcc, s68, v2
	s_nop 1
	v_addc_co_u32_e32 v5, vcc, 0, v3, vcc
	flat_store_dword v[4:5], v7
	ds_read_b32 v4, v0 offset:36896
	ds_read_b32 v5, v0 offset:41504
	v_add_co_u32_e32 v2, vcc, 0x30000, v2
	s_waitcnt lgkmcnt(0)
	v_add_f32_e32 v4, 0, v4
	v_add_f32_e32 v4, v4, v5
	ds_read_b32 v5, v0 offset:46112
	v_addc_co_u32_e32 v3, vcc, 0, v3, vcc
	s_waitcnt lgkmcnt(0)
	v_add_f32_e32 v4, v4, v5
	ds_read_b32 v5, v0 offset:50720
	s_waitcnt lgkmcnt(0)
	v_add_f32_e32 v4, v4, v5
	ds_read_b32 v5, v0 offset:55328
	s_waitcnt lgkmcnt(0)
	v_add_f32_e32 v4, v4, v5
	ds_read_b32 v5, v0 offset:59936
	s_waitcnt lgkmcnt(0)
	v_add_f32_e32 v4, v4, v5
	ds_read_b32 v5, v0 offset:64544
	s_waitcnt lgkmcnt(0)
	v_add_f32_e32 v4, v4, v5
	ds_read_b32 v5, v59 offset:36896
	s_waitcnt lgkmcnt(0)
	v_add_f32_e32 v4, v4, v5
	ds_read_b32 v5, v60 offset:36896
	s_waitcnt lgkmcnt(0)
	v_add_f32_e32 v4, v4, v5
	ds_read_b32 v5, v61 offset:36896
	s_waitcnt lgkmcnt(0)
	v_add_f32_e32 v4, v4, v5
	ds_read_b32 v5, v62 offset:36896
	s_waitcnt lgkmcnt(0)
	v_add_f32_e32 v4, v4, v5
	ds_read_b32 v5, v63 offset:36896
	s_waitcnt lgkmcnt(0)
	v_add_f32_e32 v4, v4, v5
	ds_read_b32 v5, v64 offset:36896
	s_waitcnt lgkmcnt(0)
	v_add_f32_e32 v4, v4, v5
	ds_read_b32 v5, v65 offset:36896
	s_waitcnt lgkmcnt(0)
	v_add_f32_e32 v4, v4, v5
	ds_read_b32 v5, v66 offset:36896
	s_waitcnt lgkmcnt(0)
	v_add_f32_e32 v4, v4, v5
	ds_read_b32 v5, v67 offset:36896
	s_waitcnt lgkmcnt(0)
	v_add_f32_e32 v4, v4, v5
	v_add_f32_e32 v4, v6, v4
	flat_store_dword v[2:3], v4
	s_branch .LBB0_180
